# v38 + P5 ACT stores marked nt (streamed)
# speedup vs baseline: 1.0103x; 1.0103x over previous
.LBB0_964:
	v_cvt_f32_i32_e32 v131, v118
	v_cvt_f32_i32_e32 v130, v126
	v_cvt_f32_i32_e32 v133, v114
	v_cvt_f32_i32_e32 v135, v119
	v_cvt_f32_i32_e32 v115, v115
	v_pk_mul_f32 v[130:131], v[130:131], s[8:9] op_sel_hi:[1,0]
	v_cvt_f32_i32_e32 v117, v117
	v_mul_f32_e32 v132, 0xbfb8aa3b, v130
	v_exp_f32_e32 v134, v132
	v_cvt_f32_i32_e32 v132, v122
	v_lshl_or_b32 v126, s0, 7, v184
	v_lshl_add_u32 v118, s26, 8, v182
	v_add_f32_e32 v114, 1.0, v134
	v_cvt_f32_i32_e32 v134, v127
	v_pk_mul_f32 v[132:133], v[132:133], s[8:9] op_sel_hi:[1,0]
	v_rcp_f32_e32 v114, v114
	v_mul_f32_e32 v119, 0xbfb8aa3b, v132
	v_pk_mul_f32 v[134:135], v[134:135], s[8:9] op_sel_hi:[1,0]
	v_exp_f32_e32 v119, v119
	v_mul_f32_e32 v122, 0xbfb8aa3b, v134
	v_exp_f32_e32 v122, v122
	v_mul_f32_e32 v114, v130, v114
	v_mul_f32_e32 v136, v114, v131
	v_add_f32_e32 v114, 1.0, v119
	v_rcp_f32_e32 v119, v114
	v_add_f32_e32 v114, 1.0, v122
	v_rcp_f32_e32 v122, v114
	v_cvt_f32_i32_e32 v114, v123
	v_cvt_f32_i32_e32 v123, v120
	v_mul_f32_e32 v119, v132, v119
	v_mul_f32_e32 v130, v134, v122
	v_pk_mul_f32 v[114:115], v[114:115], s[8:9] op_sel_hi:[1,0]
	v_mul_f32_e32 v120, v130, v135
	v_mul_f32_e32 v122, 0xbfb8aa3b, v114
	v_exp_f32_e32 v131, v122
	v_cvt_f32_i32_e32 v122, v128
	v_mul_f32_e32 v119, v119, v133
	s_nop 0
	v_cvt_pk_bf16_f32 v120, v136, v120
	v_add_f32_e32 v128, 1.0, v131
	v_pk_mul_f32 v[122:123], v[122:123], s[8:9] op_sel_hi:[1,0]
	v_cvt_f32_i32_e32 v131, v116
	v_mul_f32_e32 v130, 0xbfb8aa3b, v122
	v_exp_f32_e32 v132, v130
	v_cvt_f32_i32_e32 v130, v124
	v_rcp_f32_e32 v128, v128
	v_ashrrev_i32_e32 v127, 31, v126
	v_add_f32_e32 v116, 1.0, v132
	v_pk_mul_f32 v[130:131], v[130:131], s[8:9] op_sel_hi:[1,0]
	v_rcp_f32_e32 v116, v116
	v_mul_f32_e32 v124, 0xbfb8aa3b, v130
	v_exp_f32_e32 v124, v124
	v_mul_f32_e32 v114, v114, v128
	v_mul_f32_e32 v128, v114, v115
	v_mul_f32_e32 v114, v122, v116
	v_mul_f32_e32 v122, v114, v123
	v_add_f32_e32 v116, 1.0, v124
	v_cvt_f32_i32_e32 v115, v121
	v_cvt_f32_i32_e32 v114, v129
	v_rcp_f32_e32 v121, v116
	v_cvt_f32_i32_e32 v116, v125
	v_cvt_f32_i32_e32 v103, v103
	v_pk_mul_f32 v[114:115], v[114:115], s[8:9] op_sel_hi:[1,0]
	v_mul_f32_e32 v121, v130, v121
	v_mul_f32_e32 v123, 0xbfb8aa3b, v114
	v_pk_mul_f32 v[116:117], v[116:117], s[8:9] op_sel_hi:[1,0]
	v_exp_f32_e32 v123, v123
	v_mul_f32_e32 v124, 0xbfb8aa3b, v116
	v_exp_f32_e32 v124, v124
	v_mul_f32_e32 v125, v121, v131
	v_add_f32_e32 v123, 1.0, v123
	v_rcp_f32_e32 v123, v123
	v_add_f32_e32 v124, 1.0, v124
	v_rcp_f32_e32 v124, v124
	v_cvt_f32_i32_e32 v99, v99
	v_mul_f32_e32 v114, v114, v123
	v_mul_f32_e32 v114, v114, v115
	v_mul_f32_e32 v115, v116, v124
	v_mul_f32_e32 v115, v115, v117
	v_cvt_f32_i32_e32 v117, v102
	v_cvt_f32_i32_e32 v116, v110
	s_nop 0
	v_cvt_pk_bf16_f32 v121, v122, v114
	s_nop 0
	v_cvt_pk_bf16_f32 v122, v119, v128
	s_nop 0
	v_cvt_pk_bf16_f32 v123, v125, v115
	v_pk_mul_f32 v[124:125], v[116:117], s[8:9] op_sel_hi:[1,0]
	v_mov_b64_e32 v[114:115], s[12:13]
	v_mul_f32_e32 v102, 0xbfb8aa3b, v124
	v_exp_f32_e32 v102, v102
	v_mad_i64_i32 v[128:129], s[0:1], v118, s41, v[114:115]
	v_lshlrev_b64 v[116:117], 1, v[126:127]
	v_add_f32_e32 v102, 1.0, v102
	v_rcp_f32_e32 v102, v102
	v_lshl_add_u64 v[126:127], v[128:129], 0, v[116:117]
	global_store_dwordx4 v[126:127], v[120:123], off nt
	v_cvt_f32_i32_e32 v101, v101
	v_cvt_f32_i32_e32 v87, v87
	v_cvt_f32_i32_e32 v121, v98
	v_cvt_f32_i32_e32 v120, v106
	v_mul_f32_e32 v98, v124, v102
	v_cvt_f32_i32_e32 v102, v111
	v_cvt_f32_i32_e32 v83, v83
	v_pk_mul_f32 v[110:111], v[120:121], s[8:9] op_sel_hi:[1,0]
	v_mul_f32_e32 v120, v98, v125
	v_mul_f32_e32 v106, 0xbfb8aa3b, v110
	v_pk_mul_f32 v[102:103], v[102:103], s[8:9] op_sel_hi:[1,0]
	v_exp_f32_e32 v106, v106
	v_mul_f32_e32 v119, 0xbfb8aa3b, v102
	v_exp_f32_e32 v119, v119
	v_cvt_f32_i32_e32 v85, v85
	v_add_f32_e32 v98, 1.0, v106
	v_rcp_f32_e32 v106, v98
	v_add_f32_e32 v98, 1.0, v119
	v_rcp_f32_e32 v119, v98
	v_cvt_f32_i32_e32 v98, v107
	v_mul_f32_e32 v106, v110, v106
	v_mul_f32_e32 v110, v106, v111
	v_cvt_f32_i32_e32 v107, v104
	v_pk_mul_f32 v[98:99], v[98:99], s[8:9] op_sel_hi:[1,0]
	v_mul_f32_e32 v102, v102, v119
	v_mul_f32_e32 v106, 0xbfb8aa3b, v98
	v_exp_f32_e32 v111, v106
	v_cvt_f32_i32_e32 v106, v112
	v_mul_f32_e32 v104, v102, v103
	v_cvt_f32_i32_e32 v71, v71
	v_add_f32_e32 v102, 1.0, v111
	v_rcp_f32_e32 v111, v102
	v_pk_mul_f32 v[102:103], v[106:107], s[8:9] op_sel_hi:[1,0]
	v_cvt_f32_i32_e32 v107, v100
	v_mul_f32_e32 v106, 0xbfb8aa3b, v102
	v_exp_f32_e32 v112, v106
	v_cvt_f32_i32_e32 v106, v108
	v_mul_f32_e32 v98, v98, v111
	v_mul_f32_e32 v111, v98, v99
	v_add_f32_e32 v100, 1.0, v112
	v_pk_mul_f32 v[106:107], v[106:107], s[8:9] op_sel_hi:[1,0]
	v_rcp_f32_e32 v100, v100
	v_mul_f32_e32 v108, 0xbfb8aa3b, v106
	v_exp_f32_e32 v108, v108
	v_cvt_f32_i32_e32 v99, v105
	v_mul_f32_e32 v98, v102, v100
	v_mul_f32_e32 v102, v98, v103
	v_add_f32_e32 v100, 1.0, v108
	v_cvt_f32_i32_e32 v98, v113
	v_rcp_f32_e32 v103, v100
	v_cvt_f32_i32_e32 v100, v109
	v_cvt_f32_i32_e32 v67, v67
	v_pk_mul_f32 v[98:99], v[98:99], s[8:9] op_sel_hi:[1,0]
	v_mul_f32_e32 v103, v106, v103
	v_mul_f32_e32 v105, 0xbfb8aa3b, v98
	v_pk_mul_f32 v[100:101], v[100:101], s[8:9] op_sel_hi:[1,0]
	v_exp_f32_e32 v105, v105
	v_mul_f32_e32 v108, 0xbfb8aa3b, v100
	v_exp_f32_e32 v108, v108
	v_mul_f32_e32 v107, v103, v107
	v_add_f32_e32 v105, 1.0, v105
	v_rcp_f32_e32 v105, v105
	v_add_f32_e32 v106, 1.0, v108
	v_rcp_f32_e32 v106, v106
	v_cvt_f32_i32_e32 v103, v86
	v_mul_f32_e32 v98, v98, v105
	v_mul_f32_e32 v99, v98, v99
	v_mul_f32_e32 v98, v100, v106
	v_mul_f32_e32 v101, v98, v101
	s_nop 0
	v_cvt_pk_bf16_f32 v98, v120, v104
	s_nop 0
	v_cvt_pk_bf16_f32 v99, v102, v99
	v_cvt_f32_i32_e32 v102, v94
	v_or_b32_e32 v86, 16, v118
	v_mad_i64_i32 v[104:105], s[0:1], v86, s41, v[114:115]
	v_pk_mul_f32 v[102:103], v[102:103], s[8:9] op_sel_hi:[1,0]
	v_lshl_add_u64 v[104:105], v[104:105], 0, v[116:117]
	v_mul_f32_e32 v94, 0xbfb8aa3b, v102
	v_exp_f32_e32 v94, v94
	s_nop 0
	v_cvt_pk_bf16_f32 v100, v110, v111
	s_nop 0
	v_cvt_pk_bf16_f32 v101, v107, v101
	global_store_dwordx4 v[104:105], v[98:101], off nt
	v_add_f32_e32 v86, 1.0, v94
	v_rcp_f32_e32 v86, v86
	v_cvt_f32_i32_e32 v99, v82
	v_cvt_f32_i32_e32 v98, v90
	v_cvt_f32_i32_e32 v69, v69
	v_mul_f32_e32 v82, v102, v86
	v_cvt_f32_i32_e32 v86, v95
	v_pk_mul_f32 v[94:95], v[98:99], s[8:9] op_sel_hi:[1,0]
	v_mul_f32_e32 v99, v82, v103
	v_mul_f32_e32 v90, 0xbfb8aa3b, v94
	v_pk_mul_f32 v[86:87], v[86:87], s[8:9] op_sel_hi:[1,0]
	v_exp_f32_e32 v90, v90
	v_mul_f32_e32 v98, 0xbfb8aa3b, v86
	v_exp_f32_e32 v98, v98
	v_cvt_f32_i32_e32 v55, v55
	v_add_f32_e32 v82, 1.0, v90
	v_rcp_f32_e32 v90, v82
	v_add_f32_e32 v82, 1.0, v98
	v_rcp_f32_e32 v98, v82
	v_cvt_f32_i32_e32 v82, v91
	v_mul_f32_e32 v90, v94, v90
	v_mul_f32_e32 v94, v90, v95
	v_cvt_f32_i32_e32 v91, v88
	v_pk_mul_f32 v[82:83], v[82:83], s[8:9] op_sel_hi:[1,0]
	v_mul_f32_e32 v86, v86, v98
	v_mul_f32_e32 v90, 0xbfb8aa3b, v82
	v_exp_f32_e32 v95, v90
	v_cvt_f32_i32_e32 v90, v96
	v_mul_f32_e32 v88, v86, v87
	v_cvt_f32_i32_e32 v51, v51
	v_add_f32_e32 v86, 1.0, v95
	v_rcp_f32_e32 v95, v86
	v_pk_mul_f32 v[86:87], v[90:91], s[8:9] op_sel_hi:[1,0]
	v_cvt_f32_i32_e32 v91, v84
	v_mul_f32_e32 v90, 0xbfb8aa3b, v86
	v_exp_f32_e32 v96, v90
	v_cvt_f32_i32_e32 v90, v92
	v_mul_f32_e32 v82, v82, v95
	v_mul_f32_e32 v95, v82, v83
	v_add_f32_e32 v84, 1.0, v96
	v_pk_mul_f32 v[90:91], v[90:91], s[8:9] op_sel_hi:[1,0]
	v_rcp_f32_e32 v84, v84
	v_mul_f32_e32 v92, 0xbfb8aa3b, v90
	v_exp_f32_e32 v92, v92
	v_cvt_f32_i32_e32 v83, v89
	v_mul_f32_e32 v82, v86, v84
	v_mul_f32_e32 v86, v82, v87
	v_add_f32_e32 v84, 1.0, v92
	v_cvt_f32_i32_e32 v82, v97
	v_rcp_f32_e32 v87, v84
	v_cvt_f32_i32_e32 v84, v93
	v_cvt_f32_i32_e32 v53, v53
	v_pk_mul_f32 v[82:83], v[82:83], s[8:9] op_sel_hi:[1,0]
	v_mul_f32_e32 v87, v90, v87
	v_mul_f32_e32 v89, 0xbfb8aa3b, v82
	v_pk_mul_f32 v[84:85], v[84:85], s[8:9] op_sel_hi:[1,0]
	v_exp_f32_e32 v89, v89
	v_mul_f32_e32 v92, 0xbfb8aa3b, v84
	v_exp_f32_e32 v92, v92
	v_mul_f32_e32 v91, v87, v91
	v_add_f32_e32 v89, 1.0, v89
	v_rcp_f32_e32 v89, v89
	v_add_f32_e32 v90, 1.0, v92
	v_rcp_f32_e32 v90, v90
	v_cvt_f32_i32_e32 v87, v70
	v_mul_f32_e32 v82, v82, v89
	v_mul_f32_e32 v83, v82, v83
	v_mul_f32_e32 v82, v84, v90
	v_mul_f32_e32 v85, v82, v85
	s_nop 0
	v_cvt_pk_bf16_f32 v82, v99, v88
	s_nop 0
	v_cvt_pk_bf16_f32 v83, v86, v83
	v_cvt_f32_i32_e32 v86, v78
	v_or_b32_e32 v70, 32, v118
	v_mad_i64_i32 v[88:89], s[0:1], v70, s41, v[114:115]
	v_pk_mul_f32 v[86:87], v[86:87], s[8:9] op_sel_hi:[1,0]
	v_lshl_add_u64 v[88:89], v[88:89], 0, v[116:117]
	v_mul_f32_e32 v78, 0xbfb8aa3b, v86
	v_exp_f32_e32 v78, v78
	s_nop 0
	v_cvt_pk_bf16_f32 v84, v94, v95
	s_nop 0
	v_cvt_pk_bf16_f32 v85, v91, v85
	global_store_dwordx4 v[88:89], v[82:85], off nt
	v_add_f32_e32 v70, 1.0, v78
	v_rcp_f32_e32 v70, v70
	v_cvt_f32_i32_e32 v83, v66
	v_cvt_f32_i32_e32 v82, v74
	v_cvt_f32_i32_e32 v39, v39
	v_mul_f32_e32 v66, v86, v70
	v_cvt_f32_i32_e32 v70, v79
	v_pk_mul_f32 v[78:79], v[82:83], s[8:9] op_sel_hi:[1,0]
	v_mul_f32_e32 v83, v66, v87
	v_mul_f32_e32 v74, 0xbfb8aa3b, v78
	v_pk_mul_f32 v[70:71], v[70:71], s[8:9] op_sel_hi:[1,0]
	v_exp_f32_e32 v74, v74
	v_mul_f32_e32 v82, 0xbfb8aa3b, v70
	v_exp_f32_e32 v82, v82
	v_cvt_f32_i32_e32 v35, v35
	v_add_f32_e32 v66, 1.0, v74
	v_rcp_f32_e32 v74, v66
	v_add_f32_e32 v66, 1.0, v82
	v_rcp_f32_e32 v82, v66
	v_cvt_f32_i32_e32 v66, v75
	v_mul_f32_e32 v74, v78, v74
	v_mul_f32_e32 v78, v74, v79
	v_cvt_f32_i32_e32 v75, v72
	v_pk_mul_f32 v[66:67], v[66:67], s[8:9] op_sel_hi:[1,0]
	v_mul_f32_e32 v70, v70, v82
	v_mul_f32_e32 v74, 0xbfb8aa3b, v66
	v_exp_f32_e32 v79, v74
	v_cvt_f32_i32_e32 v74, v80
	v_mul_f32_e32 v72, v70, v71
	v_cvt_f32_i32_e32 v37, v37
	v_add_f32_e32 v70, 1.0, v79
	v_rcp_f32_e32 v79, v70
	v_pk_mul_f32 v[70:71], v[74:75], s[8:9] op_sel_hi:[1,0]
	v_cvt_f32_i32_e32 v75, v68
	v_mul_f32_e32 v74, 0xbfb8aa3b, v70
	v_exp_f32_e32 v80, v74
	v_cvt_f32_i32_e32 v74, v76
	v_mul_f32_e32 v66, v66, v79
	v_mul_f32_e32 v79, v66, v67
	v_add_f32_e32 v68, 1.0, v80
	v_pk_mul_f32 v[74:75], v[74:75], s[8:9] op_sel_hi:[1,0]
	v_rcp_f32_e32 v68, v68
	v_mul_f32_e32 v76, 0xbfb8aa3b, v74
	v_exp_f32_e32 v76, v76
	v_cvt_f32_i32_e32 v67, v73
	v_mul_f32_e32 v66, v70, v68
	v_mul_f32_e32 v70, v66, v71
	v_add_f32_e32 v68, 1.0, v76
	v_cvt_f32_i32_e32 v66, v81
	v_rcp_f32_e32 v71, v68
	v_cvt_f32_i32_e32 v68, v77
	v_cvt_f32_i32_e32 v23, v23
	v_pk_mul_f32 v[66:67], v[66:67], s[8:9] op_sel_hi:[1,0]
	v_mul_f32_e32 v71, v74, v71
	v_mul_f32_e32 v73, 0xbfb8aa3b, v66
	v_pk_mul_f32 v[68:69], v[68:69], s[8:9] op_sel_hi:[1,0]
	v_exp_f32_e32 v73, v73
	v_mul_f32_e32 v76, 0xbfb8aa3b, v68
	v_exp_f32_e32 v76, v76
	v_mul_f32_e32 v75, v71, v75
	v_add_f32_e32 v73, 1.0, v73
	v_rcp_f32_e32 v73, v73
	v_add_f32_e32 v74, 1.0, v76
	v_rcp_f32_e32 v74, v74
	v_cvt_f32_i32_e32 v71, v54
	v_mul_f32_e32 v66, v66, v73
	v_mul_f32_e32 v67, v66, v67
	v_mul_f32_e32 v66, v68, v74
	v_mul_f32_e32 v69, v66, v69
	s_nop 0
	v_cvt_pk_bf16_f32 v66, v83, v72
	s_nop 0
	v_cvt_pk_bf16_f32 v67, v70, v67
	v_cvt_f32_i32_e32 v70, v62
	v_or_b32_e32 v54, 48, v118
	v_mad_i64_i32 v[72:73], s[0:1], v54, s41, v[114:115]
	v_pk_mul_f32 v[70:71], v[70:71], s[8:9] op_sel_hi:[1,0]
	v_lshl_add_u64 v[72:73], v[72:73], 0, v[116:117]
	v_mul_f32_e32 v62, 0xbfb8aa3b, v70
	v_exp_f32_e32 v62, v62
	s_nop 0
	v_cvt_pk_bf16_f32 v68, v78, v79
	s_nop 0
	v_cvt_pk_bf16_f32 v69, v75, v69
	global_store_dwordx4 v[72:73], v[66:69], off nt
	v_add_f32_e32 v54, 1.0, v62
	v_rcp_f32_e32 v54, v54
	v_cvt_f32_i32_e32 v67, v50
	v_cvt_f32_i32_e32 v66, v58
	v_add_u32_e32 v68, 0x80, v118
	v_mul_f32_e32 v50, v70, v54
	v_cvt_f32_i32_e32 v54, v63
	v_pk_mul_f32 v[62:63], v[66:67], s[8:9] op_sel_hi:[1,0]
	v_mul_f32_e32 v67, v50, v71
	v_mul_f32_e32 v58, 0xbfb8aa3b, v62
	v_pk_mul_f32 v[54:55], v[54:55], s[8:9] op_sel_hi:[1,0]
	v_exp_f32_e32 v58, v58
	v_mul_f32_e32 v66, 0xbfb8aa3b, v54
	v_exp_f32_e32 v66, v66
	v_cvt_f32_i32_e32 v19, v19
	v_add_f32_e32 v50, 1.0, v58
	v_rcp_f32_e32 v58, v50
	v_add_f32_e32 v50, 1.0, v66
	v_rcp_f32_e32 v66, v50
	v_cvt_f32_i32_e32 v50, v59
	v_mul_f32_e32 v58, v62, v58
	v_mul_f32_e32 v62, v58, v63
	v_cvt_f32_i32_e32 v59, v56
	v_pk_mul_f32 v[50:51], v[50:51], s[8:9] op_sel_hi:[1,0]
	v_mul_f32_e32 v54, v54, v66
	v_mul_f32_e32 v58, 0xbfb8aa3b, v50
	v_exp_f32_e32 v63, v58
	v_cvt_f32_i32_e32 v58, v64
	v_mul_f32_e32 v56, v54, v55
	v_cvt_f32_i32_e32 v21, v21
	v_add_f32_e32 v54, 1.0, v63
	v_rcp_f32_e32 v63, v54
	v_pk_mul_f32 v[54:55], v[58:59], s[8:9] op_sel_hi:[1,0]
	v_cvt_f32_i32_e32 v59, v52
	v_mul_f32_e32 v58, 0xbfb8aa3b, v54
	v_exp_f32_e32 v64, v58
	v_mul_f32_e32 v50, v50, v63
	v_cvt_f32_i32_e32 v58, v60
	v_mul_f32_e32 v63, v50, v51
	v_add_f32_e32 v52, 1.0, v64
	v_rcp_f32_e32 v52, v52
	v_cvt_f32_i32_e32 v51, v57
	v_pk_mul_f32 v[58:59], v[58:59], s[8:9] op_sel_hi:[1,0]
	v_cvt_f32_i32_e32 v7, v7
	v_mul_f32_e32 v50, v54, v52
	v_mul_f32_e32 v64, v50, v55
	v_cvt_f32_i32_e32 v50, v65
	v_mul_f32_e32 v60, 0xbfb8aa3b, v58
	v_exp_f32_e32 v60, v60
	v_cvt_f32_i32_e32 v3, v3
	v_pk_mul_f32 v[50:51], v[50:51], s[8:9] op_sel_hi:[1,0]
	v_cvt_f32_i32_e32 v5, v5
	v_mul_f32_e32 v55, 0xbfb8aa3b, v50
	v_exp_f32_e32 v55, v55
	v_add_f32_e32 v52, 1.0, v60
	v_rcp_f32_e32 v54, v52
	v_cvt_f32_i32_e32 v52, v61
	v_add_f32_e32 v55, 1.0, v55
	v_rcp_f32_e32 v55, v55
	v_mul_f32_e32 v54, v58, v54
	v_pk_mul_f32 v[52:53], v[52:53], s[8:9] op_sel_hi:[1,0]
	v_mul_f32_e32 v58, v54, v59
	v_mul_f32_e32 v50, v50, v55
	v_cvt_f32_i32_e32 v55, v38
	v_cvt_f32_i32_e32 v54, v46
	v_mul_f32_e32 v57, 0xbfb8aa3b, v52
	v_exp_f32_e32 v57, v57
	v_mul_f32_e32 v51, v50, v51
	v_pk_mul_f32 v[54:55], v[54:55], s[8:9] op_sel_hi:[1,0]
	s_andn2_b64 vcc, exec, s[20:21]
	v_mul_f32_e32 v38, 0xbfb8aa3b, v54
	v_add_f32_e32 v57, 1.0, v57
	v_exp_f32_e32 v38, v38
	v_rcp_f32_e32 v57, v57
	s_mov_b64 s[20:21], -1
	v_add_f32_e32 v38, 1.0, v38
	v_mul_f32_e32 v50, v52, v57
	v_rcp_f32_e32 v38, v38
	v_mul_f32_e32 v53, v50, v53
	s_nop 0
	v_cvt_pk_bf16_f32 v50, v67, v56
	v_mad_i64_i32 v[56:57], s[0:1], v68, s41, v[114:115]
	s_nop 0
	v_cvt_pk_bf16_f32 v51, v64, v51
	v_lshl_add_u64 v[56:57], v[56:57], 0, v[116:117]
	s_nop 0
	v_cvt_pk_bf16_f32 v52, v62, v63
	s_nop 0
	v_cvt_pk_bf16_f32 v53, v58, v53
	global_store_dwordx4 v[56:57], v[50:53], off nt
	s_nop 1
	v_cvt_f32_i32_e32 v51, v34
	v_cvt_f32_i32_e32 v50, v42
	v_mul_f32_e32 v34, v54, v38
	v_cvt_f32_i32_e32 v38, v47
	v_pk_mul_f32 v[46:47], v[50:51], s[8:9] op_sel_hi:[1,0]
	s_nop 0
	v_mul_f32_e32 v42, 0xbfb8aa3b, v46
	v_pk_mul_f32 v[38:39], v[38:39], s[8:9] op_sel_hi:[1,0]
	v_exp_f32_e32 v42, v42
	v_mul_f32_e32 v50, 0xbfb8aa3b, v38
	v_exp_f32_e32 v50, v50
	v_mul_f32_e32 v51, v34, v55
	v_add_f32_e32 v34, 1.0, v42
	v_rcp_f32_e32 v42, v34
	v_add_f32_e32 v34, 1.0, v50
	v_rcp_f32_e32 v50, v34
	v_cvt_f32_i32_e32 v34, v43
	v_mul_f32_e32 v42, v46, v42
	v_mul_f32_e32 v46, v42, v47
	v_cvt_f32_i32_e32 v43, v40
	v_pk_mul_f32 v[34:35], v[34:35], s[8:9] op_sel_hi:[1,0]
	v_mul_f32_e32 v38, v38, v50
	v_mul_f32_e32 v42, 0xbfb8aa3b, v34
	v_exp_f32_e32 v47, v42
	v_cvt_f32_i32_e32 v42, v48
	v_mul_f32_e32 v40, v38, v39
	v_add_f32_e32 v38, 1.0, v47
	v_rcp_f32_e32 v47, v38
	v_pk_mul_f32 v[38:39], v[42:43], s[8:9] op_sel_hi:[1,0]
	v_cvt_f32_i32_e32 v43, v36
	v_mul_f32_e32 v42, 0xbfb8aa3b, v38
	v_exp_f32_e32 v48, v42
	v_cvt_f32_i32_e32 v42, v44
	v_mul_f32_e32 v34, v34, v47
	v_mul_f32_e32 v47, v34, v35
	v_add_f32_e32 v36, 1.0, v48
	v_pk_mul_f32 v[42:43], v[42:43], s[8:9] op_sel_hi:[1,0]
	v_rcp_f32_e32 v36, v36
	v_mul_f32_e32 v44, 0xbfb8aa3b, v42
	v_exp_f32_e32 v44, v44
	v_cvt_f32_i32_e32 v35, v41
	v_mul_f32_e32 v34, v38, v36
	v_mul_f32_e32 v38, v34, v39
	v_add_f32_e32 v36, 1.0, v44
	v_cvt_f32_i32_e32 v34, v49
	v_rcp_f32_e32 v39, v36
	v_cvt_f32_i32_e32 v36, v45
	v_pk_mul_f32 v[34:35], v[34:35], s[8:9] op_sel_hi:[1,0]
	s_nop 0
	v_mul_f32_e32 v41, 0xbfb8aa3b, v34
	v_pk_mul_f32 v[36:37], v[36:37], s[8:9] op_sel_hi:[1,0]
	v_exp_f32_e32 v41, v41
	v_mul_f32_e32 v44, 0xbfb8aa3b, v36
	v_exp_f32_e32 v44, v44
	v_mul_f32_e32 v39, v42, v39
	v_add_f32_e32 v41, 1.0, v41
	v_rcp_f32_e32 v41, v41
	v_add_f32_e32 v42, 1.0, v44
	v_rcp_f32_e32 v42, v42
	v_mul_f32_e32 v43, v39, v43
	v_mul_f32_e32 v34, v34, v41
	v_mul_f32_e32 v35, v34, v35
	v_mul_f32_e32 v34, v36, v42
	v_mul_f32_e32 v37, v34, v37
	s_nop 0
	v_cvt_pk_bf16_f32 v34, v51, v40
	s_nop 0
	v_cvt_pk_bf16_f32 v35, v38, v35
	v_cvt_f32_i32_e32 v39, v22
	v_cvt_f32_i32_e32 v38, v30
	v_add_u32_e32 v22, 0x90, v118
	v_mad_i64_i32 v[40:41], s[0:1], v22, s41, v[114:115]
	v_pk_mul_f32 v[38:39], v[38:39], s[8:9] op_sel_hi:[1,0]
	v_lshl_add_u64 v[40:41], v[40:41], 0, v[116:117]
	v_mul_f32_e32 v30, 0xbfb8aa3b, v38
	v_exp_f32_e32 v30, v30
	s_nop 0
	v_cvt_pk_bf16_f32 v36, v46, v47
	s_nop 0
	v_cvt_pk_bf16_f32 v37, v43, v37
	global_store_dwordx4 v[40:41], v[34:37], off nt
	v_add_f32_e32 v22, 1.0, v30
	v_rcp_f32_e32 v22, v22
	v_cvt_f32_i32_e32 v35, v18
	v_cvt_f32_i32_e32 v34, v26
	v_mul_f32_e32 v18, v38, v22
	v_cvt_f32_i32_e32 v22, v31
	v_pk_mul_f32 v[30:31], v[34:35], s[8:9] op_sel_hi:[1,0]
	v_mul_f32_e32 v35, v18, v39
	v_mul_f32_e32 v26, 0xbfb8aa3b, v30
	v_pk_mul_f32 v[22:23], v[22:23], s[8:9] op_sel_hi:[1,0]
	v_exp_f32_e32 v26, v26
	v_mul_f32_e32 v34, 0xbfb8aa3b, v22
	v_exp_f32_e32 v34, v34
	v_add_f32_e32 v18, 1.0, v26
	v_rcp_f32_e32 v26, v18
	v_add_f32_e32 v18, 1.0, v34
	v_rcp_f32_e32 v34, v18
	v_cvt_f32_i32_e32 v18, v27
	v_mul_f32_e32 v26, v30, v26
	v_mul_f32_e32 v30, v26, v31
	v_cvt_f32_i32_e32 v27, v24
	v_pk_mul_f32 v[18:19], v[18:19], s[8:9] op_sel_hi:[1,0]
	v_mul_f32_e32 v22, v22, v34
	v_mul_f32_e32 v26, 0xbfb8aa3b, v18
	v_exp_f32_e32 v31, v26
	v_cvt_f32_i32_e32 v26, v32
	v_mul_f32_e32 v24, v22, v23
	v_add_f32_e32 v22, 1.0, v31
	v_rcp_f32_e32 v31, v22
	v_pk_mul_f32 v[22:23], v[26:27], s[8:9] op_sel_hi:[1,0]
	v_cvt_f32_i32_e32 v27, v20
	v_mul_f32_e32 v26, 0xbfb8aa3b, v22
	v_exp_f32_e32 v32, v26
	v_cvt_f32_i32_e32 v26, v28
	v_mul_f32_e32 v18, v18, v31
	v_mul_f32_e32 v31, v18, v19
	v_add_f32_e32 v20, 1.0, v32
	v_pk_mul_f32 v[26:27], v[26:27], s[8:9] op_sel_hi:[1,0]
	v_rcp_f32_e32 v20, v20
	v_mul_f32_e32 v28, 0xbfb8aa3b, v26
	v_exp_f32_e32 v28, v28
	v_cvt_f32_i32_e32 v19, v25
	v_mul_f32_e32 v18, v22, v20
	v_mul_f32_e32 v22, v18, v23
	v_add_f32_e32 v20, 1.0, v28
	v_cvt_f32_i32_e32 v18, v33
	v_rcp_f32_e32 v23, v20
	v_cvt_f32_i32_e32 v20, v29
	v_pk_mul_f32 v[18:19], v[18:19], s[8:9] op_sel_hi:[1,0]
	s_nop 0
	v_mul_f32_e32 v25, 0xbfb8aa3b, v18
	v_pk_mul_f32 v[20:21], v[20:21], s[8:9] op_sel_hi:[1,0]
	v_exp_f32_e32 v25, v25
	v_mul_f32_e32 v28, 0xbfb8aa3b, v20
	v_exp_f32_e32 v28, v28
	v_mul_f32_e32 v23, v26, v23
	v_add_f32_e32 v25, 1.0, v25
	v_rcp_f32_e32 v25, v25
	v_add_f32_e32 v26, 1.0, v28
	v_rcp_f32_e32 v26, v26
	v_mul_f32_e32 v27, v23, v27
	v_mul_f32_e32 v18, v18, v25
	v_mul_f32_e32 v19, v18, v19
	v_mul_f32_e32 v18, v20, v26
	v_mul_f32_e32 v21, v18, v21
	s_nop 0
	v_cvt_pk_bf16_f32 v18, v35, v24
	s_nop 0
	v_cvt_pk_bf16_f32 v19, v22, v19
	v_cvt_f32_i32_e32 v23, v6
	v_cvt_f32_i32_e32 v22, v14
	v_add_u32_e32 v6, 0xa0, v118
	v_mad_i64_i32 v[24:25], s[0:1], v6, s41, v[114:115]
	v_pk_mul_f32 v[22:23], v[22:23], s[8:9] op_sel_hi:[1,0]
	v_lshl_add_u64 v[24:25], v[24:25], 0, v[116:117]
	v_mul_f32_e32 v14, 0xbfb8aa3b, v22
	v_exp_f32_e32 v14, v14
	s_nop 0
	v_cvt_pk_bf16_f32 v20, v30, v31
	s_nop 0
	v_cvt_pk_bf16_f32 v21, v27, v21
	global_store_dwordx4 v[24:25], v[18:21], off nt
	v_add_f32_e32 v6, 1.0, v14
	v_rcp_f32_e32 v6, v6
	v_cvt_f32_i32_e32 v19, v2
	v_cvt_f32_i32_e32 v18, v10
	v_mul_f32_e32 v2, v22, v6
	v_cvt_f32_i32_e32 v6, v15
	v_pk_mul_f32 v[14:15], v[18:19], s[8:9] op_sel_hi:[1,0]
	v_mul_f32_e32 v19, v2, v23
	v_mul_f32_e32 v10, 0xbfb8aa3b, v14
	v_pk_mul_f32 v[6:7], v[6:7], s[8:9] op_sel_hi:[1,0]
	v_exp_f32_e32 v10, v10
	v_mul_f32_e32 v18, 0xbfb8aa3b, v6
	v_exp_f32_e32 v18, v18
	v_add_f32_e32 v2, 1.0, v10
	v_rcp_f32_e32 v10, v2
	v_add_f32_e32 v2, 1.0, v18
	v_rcp_f32_e32 v18, v2
	v_cvt_f32_i32_e32 v2, v11
	v_mul_f32_e32 v10, v14, v10
	v_mul_f32_e32 v14, v10, v15
	v_cvt_f32_i32_e32 v11, v8
	v_pk_mul_f32 v[2:3], v[2:3], s[8:9] op_sel_hi:[1,0]
	v_mul_f32_e32 v6, v6, v18
	v_mul_f32_e32 v10, 0xbfb8aa3b, v2
	v_exp_f32_e32 v15, v10
	v_cvt_f32_i32_e32 v10, v16
	v_mul_f32_e32 v8, v6, v7
	v_add_f32_e32 v6, 1.0, v15
	v_rcp_f32_e32 v15, v6
	v_pk_mul_f32 v[6:7], v[10:11], s[8:9] op_sel_hi:[1,0]
	v_cvt_f32_i32_e32 v11, v4
	v_mul_f32_e32 v10, 0xbfb8aa3b, v6
	v_exp_f32_e32 v16, v10
	v_cvt_f32_i32_e32 v10, v12
	v_mul_f32_e32 v2, v2, v15
	v_mul_f32_e32 v15, v2, v3
	v_add_f32_e32 v4, 1.0, v16
	v_pk_mul_f32 v[10:11], v[10:11], s[8:9] op_sel_hi:[1,0]
	v_rcp_f32_e32 v4, v4
	v_mul_f32_e32 v12, 0xbfb8aa3b, v10
	v_exp_f32_e32 v12, v12
	v_cvt_f32_i32_e32 v3, v9
	v_mul_f32_e32 v2, v6, v4
	v_mul_f32_e32 v6, v2, v7
	v_add_f32_e32 v4, 1.0, v12
	v_cvt_f32_i32_e32 v2, v17
	v_rcp_f32_e32 v7, v4
	v_cvt_f32_i32_e32 v4, v13
	v_pk_mul_f32 v[2:3], v[2:3], s[8:9] op_sel_hi:[1,0]
	s_nop 0
	v_mul_f32_e32 v9, 0xbfb8aa3b, v2
	v_pk_mul_f32 v[4:5], v[4:5], s[8:9] op_sel_hi:[1,0]
	v_exp_f32_e32 v9, v9
	v_mul_f32_e32 v12, 0xbfb8aa3b, v4
	v_exp_f32_e32 v12, v12
	v_mul_f32_e32 v7, v10, v7
	v_add_f32_e32 v9, 1.0, v9
	v_rcp_f32_e32 v9, v9
	v_add_f32_e32 v10, 1.0, v12
	v_rcp_f32_e32 v10, v10
	v_mul_f32_e32 v7, v7, v11
	v_mul_f32_e32 v2, v2, v9
	v_mul_f32_e32 v3, v2, v3
	v_mul_f32_e32 v2, v4, v10
	v_mul_f32_e32 v5, v2, v5
	s_nop 0
	v_cvt_pk_bf16_f32 v2, v19, v8
	s_nop 0
	v_cvt_pk_bf16_f32 v3, v6, v3
	v_add_u32_e32 v6, 0xb0, v118
	s_nop 0
	v_cvt_pk_bf16_f32 v4, v14, v15
	s_nop 0
	v_cvt_pk_bf16_f32 v5, v7, v5
	v_mad_i64_i32 v[6:7], s[0:1], v6, s41, v[114:115]
	v_lshl_add_u64 v[6:7], v[6:7], 0, v[116:117]
	global_store_dwordx4 v[6:7], v[2:5], off nt
	s_cbranch_vccnz .LBB0_957
	s_andn2_b64 vcc, exec, s[2:3]
	s_cbranch_vccnz .LBB0_956
	s_barrier
	s_branch .LBB0_956
